# attention tile loop back edge rotated: parity / K read base / last-tile flag computed before the barrier, K fragment reads first after it, tile loads after them
# speedup vs baseline: 1.0015x; 1.0015x over previous
; #define MFMA32(a, b, c) __builtin_amdgcn_mfma_f32_32x32x16_bf16((a), (b), (c), 0, 0, 0)
; #define STOREKV(buf) do { *(u32x4*)(Kt + (buf) * KT_BYTES + kr0 * KROW + kc0 * 16) = xk0; \
;         if (tid < 256) { *(u32x4*)(Kt + (buf) * KT_BYTES + kr1 * KROW + kc1 * 16) = xa; } \
;         else { tstore_pair(Vt + (buf) * VT_BYTES, VROW, pos64(2 * va), vc8, xa, xb); } } while (0)
; __device__ __forceinline__ void attn_unit2(const bf16_t* Qm, const bf16_t* KVm, const bf16_t* P1, bf16_t* OP, int q0, int h, int klat, int nlat, int kctx, int nt, uchar* lds, bool nostore = false) {
;     ...
;     LOADKV(0); STOREKV(0);
;     __syncthreads();
;     float mA = -1e30f, mB = -1e30f, lA = 0.f, lB = 0.f; f32x16 oA0 = {}, oA1 = {}, oB0 = {}, oB1 = {};
;     for (int t = 0; t < nt; ++t) {
;         const int buf = t & 1;
;         if (t + 1 < nt) LOADKV(t + 1);
;         f32x16 sA0 = {}, sA1 = {}, sB0 = {}, sB1 = {};
;         { const uchar* kb = Kt + buf * KT_BYTES + l32 * KROW + hi * 16;
; #pragma unroll
;           for (int s = 0; s < 6; ++s) { const bf16x8 a0 = *(const bf16x8*)(kb + s * 32), a1 = *(const bf16x8*)(kb + 32 * KROW + s * 32);
;               sA0 = MFMA32(a0, qa[s], sA0); sA1 = MFMA32(a1, qa[s], sA1); sB0 = MFMA32(a0, qb[s], sB0); sB1 = MFMA32(a1, qb[s], sB1); } }
;     ...
;         if (t + 1 < nt) STOREKV(buf ^ 1);
;         __syncthreads();
.LBB0_1102:
	v_add_f32_e32 v198, v200, v198
	v_add_f32_e32 v200, v80, v81
	v_add_f32_e32 v198, v200, v198
	v_add_f32_e32 v229, v229, v198
	s_add_i32 s9, s9, 1
	s_add_i32 s13, s13, 64
	s_add_i32 s22, s22, 64
	v_add_f32_e32 v231, v231, v199
	s_cmpk_lg_i32 s9, 0x83
	s_cselect_b64 s[44:45], -1, 0
	s_and_b32 s4, s9, 1
	s_mul_i32 s5, s4, 0x3400
	v_add_u32_e32 v0, s5, v226
	s_cmpk_eq_i32 s9, 0x84
	s_waitcnt lgkmcnt(0)
	s_barrier
	s_cbranch_scc1 .LBB0_1126
	s_branch .Latt_head
.LBB0_1103:
	s_cmpk_lg_i32 s9, 0x83
	s_cselect_b64 s[44:45], -1, 0
	s_and_b32 s4, s9, 1
	s_mul_i32 s5, s4, 0x3400
	v_add_u32_e32 v0, s5, v226
.Latt_head:
	ds_read_b128 v[66:69], v0
	ds_read_b128 v[70:73], v0 offset:32
	ds_read_b128 v[74:77], v0 offset:6656
	ds_read_b128 v[234:237], v0 offset:6688
	s_cmpk_eq_i32 s9, 0x83
	s_cbranch_scc1 .Latt_lddone
	s_cmpk_lt_u32 s9, 0x7f
	s_cselect_b32 s6, s22, s13
	s_mul_i32 s18, s6, s16
	s_add_u32 s18, s18, s82
	s_addc_u32 s19, s83, 0
	s_add_u32 s18, s18, s30
	s_addc_u32 s19, s19, s31
	s_lshl_b32 s6, s6, 11
	s_add_u32 s6, s6, s74
	s_add_u32 s6, s92, s6
	s_addc_u32 s7, s93, 0
	s_mov_b64 exec, s[38:39]
	global_load_dwordx4 v[178:181], v196, s[18:19]
	s_not_b64 exec, exec
	global_load_dwordx4 v[178:181], v196, s[6:7]
	s_cmp_lg_u64 s[40:41], 0
	s_cbranch_scc1 .Latt_ldv
	s_mov_b64 exec, s[42:43]
	global_load_dwordx4 v[186:189], v197, s[18:19]
	s_not_b64 exec, exec
	global_load_dwordx4 v[186:189], v197, s[6:7]
	s_branch .Latt_lddone

; #define MFMA32(a, b, c) __builtin_amdgcn_mfma_f32_32x32x16_bf16((a), (b), (c), 0, 0, 0)
; __device__ __forceinline__ void attn_unit2(const bf16_t* Qm, const bf16_t* KVm, const bf16_t* P1, bf16_t* OP, int q0, int h, int klat, int nlat, int kctx, int nt, uchar* lds, bool nostore = false) {
;     ...
;         { const uchar* kb = Kt + buf * KT_BYTES + l32 * KROW + hi * 16;
; #pragma unroll
;           for (int s = 0; s < 6; ++s) { const bf16x8 a0 = *(const bf16x8*)(kb + s * 32), a1 = *(const bf16x8*)(kb + 32 * KROW + s * 32);
;               sA0 = MFMA32(a0, qa[s], sA0); sA1 = MFMA32(a1, qa[s], sA1); sB0 = MFMA32(a0, qb[s], sB0); sB1 = MFMA32(a1, qb[s], sB1); } }
.LBB0_1117:
	v_mfma_f32_32x32x16_bf16 v[114:129], v[208:211], v[216:219], 0
	v_mfma_f32_32x32x16_bf16 v[98:113], v[208:211], v[190:193], 0
	s_waitcnt lgkmcnt(3)
	v_mfma_f32_32x32x16_bf16 v[114:129], v[66:69], v[130:133], v[114:129]
	v_mfma_f32_32x32x16_bf16 v[98:113], v[66:69], v[170:173], v[98:113]
	s_waitcnt lgkmcnt(2)
	v_mfma_f32_32x32x16_bf16 v[114:129], v[70:73], v[134:137], v[114:129]
	v_mfma_f32_32x32x16_bf16 v[98:113], v[70:73], v[138:141], v[98:113]
	ds_read_b128 v[66:69], v0 offset:64
	ds_read_b128 v[70:73], v0 offset:96
	ds_read_b128 v[238:241], v0 offset:6720
	ds_read_b128 v[242:245], v0 offset:6752
	s_waitcnt lgkmcnt(3)
	v_mfma_f32_32x32x16_bf16 v[114:129], v[66:69], v[146:149], v[114:129]
	v_mfma_f32_32x32x16_bf16 v[98:113], v[66:69], v[142:145], v[98:113]
	v_mfma_f32_32x32x16_bf16 v[82:97], v[208:211], v[216:219], 0
	v_mfma_f32_32x32x16_bf16 v[82:97], v[74:77], v[130:133], v[82:97]
	s_waitcnt lgkmcnt(2)
	v_mfma_f32_32x32x16_bf16 v[114:129], v[70:73], v[150:153], v[114:129]
	v_mfma_f32_32x32x16_bf16 v[98:113], v[70:73], v[154:157], v[98:113]
	ds_read_b128 v[66:69], v0 offset:128
	ds_read_b128 v[70:73], v0 offset:160
	ds_read_b128 v[246:249], v0 offset:6784
	ds_read_b128 v[212:215], v0 offset:6816
	v_mfma_f32_32x32x16_bf16 v[82:97], v[234:237], v[134:137], v[82:97]
	s_waitcnt lgkmcnt(3)
	v_mfma_f32_32x32x16_bf16 v[114:129], v[66:69], v[162:165], v[114:129]
	v_mfma_f32_32x32x16_bf16 v[98:113], v[66:69], v[158:161], v[98:113]
	v_mfma_f32_32x32x16_bf16 v[82:97], v[238:241], v[146:149], v[82:97]
	s_waitcnt lgkmcnt(2)
	v_mfma_f32_32x32x16_bf16 v[114:129], v[70:73], v[166:169], v[114:129]
	v_mfma_f32_32x32x16_bf16 v[98:113], v[70:73], v[174:177], v[98:113]
	s_nop 10
	v_max_f32_e32 v0, v115, v115
	v_mfma_f32_32x32x16_bf16 v[66:81], v[74:77], v[170:173], 0
	v_mfma_f32_32x32x16_bf16 v[66:81], v[208:211], v[190:193], v[66:81]
	v_mfma_f32_32x32x16_bf16 v[82:97], v[242:245], v[150:153], v[82:97]
	v_mfma_f32_32x32x16_bf16 v[66:81], v[234:237], v[138:141], v[66:81]
	v_max_f32_e32 v234, v114, v114
	v_max_f32_e32 v0, v234, v0
	s_waitcnt lgkmcnt(1)
	v_mfma_f32_32x32x16_bf16 v[82:97], v[246:249], v[162:165], v[82:97]
	v_mfma_f32_32x32x16_bf16 v[66:81], v[238:241], v[142:145], v[66:81]
	s_waitcnt lgkmcnt(0)
	v_mfma_f32_32x32x16_bf16 v[82:97], v[212:215], v[166:169], v[82:97]
	v_mfma_f32_32x32x16_bf16 v[66:81], v[242:245], v[154:157], v[66:81]
	s_nop 10
	v_max3_f32 v234, v116, v117, v83
	v_max3_f32 v0, v0, v82, v84
	v_max3_f32 v0, v0, v85, v118
	v_max3_f32 v234, v234, v120, v121
	v_max3_f32 v0, v0, v119, v86
	v_max3_f32 v234, v234, v88, v89
	v_max3_f32 v0, v0, v87, v122
	v_mfma_f32_32x32x16_bf16 v[66:81], v[246:249], v[158:161], v[66:81]
	v_mfma_f32_32x32x16_bf16 v[66:81], v[212:215], v[174:177], v[66:81]
	v_max3_f32 v234, v234, v124, v125
	v_max3_f32 v0, v0, v123, v90
	v_max3_f32 v234, v234, v92, v93
	v_max3_f32 v0, v0, v91, v126
	v_max3_f32 v234, v234, v128, v129
	v_max3_f32 v0, v0, v127, v94
	v_max3_f32 v234, v234, v96, v97
	v_max3_f32 v0, v0, v95, v234
	v_max3_f32 v235, v98, v99, v100
	v_max3_f32 v236, v101, v102, v103
	v_max3_f32 v235, v235, v104, v105
	v_max3_f32 v236, v236, v106, v107
	v_max3_f32 v235, v235, v108, v109
	v_max3_f32 v236, v236, v110, v111
	v_max3_f32 v235, v235, v112, v113
	v_max3_f32 v236, v236, v66, v67
	v_max3_f32 v235, v235, v68, v69
	v_max3_f32 v236, v236, v70, v71
	v_max3_f32 v235, v235, v72, v73
	v_max3_f32 v236, v236, v74, v75
	v_max3_f32 v235, v235, v76, v77
	v_max3_f32 v236, v236, v78, v79
	v_max3_f32 v235, v235, v80, v81
	v_max_f32_e32 v235, v235, v236
	v_max_f32_e32 v236, v0, v235
	v_cmp_lt_f32_e32 vcc, 0x41000000, v236
	s_cmp_eq_u32 s9, 0
	s_cbranch_scc1 .Latt_rare
	s_cbranch_vccz .LBB0_1121
